# GSWI/GINPROJ tile mapping: group-height division replaced by shift (heights are 8 or 4); GSWI epilogue row-block addresses by constant 64-bit adds
# baseline (speedup 1.0000x reference)
;     __host__ __device__ bool next(int i, Unit& u) const {
;         const long L = (long)i * G + c; if (L >= nwg) return false;
;         if (sl) { if (i > 0) return false; u.pm = ((int)L & 15) >> 2; u.pn = (int)L & 3; return true; }
;         int wgid = (int)L; { const int q = nwg / NXCD, r = nwg % NXCD, xcd = wgid % NXCD, off = wgid / NXCD; wgid = (xcd < r ? xcd * (q + 1) : r * (q + 1) + (xcd - r) * q) + off; }
;         const int nig = WGM * nN, gid = wgid / nig, fm = gid * WGM, gsz = (nM - fm) < WGM ? (nM - fm) : WGM;
;         u.pm = fm + ((wgid % nig) % gsz); u.pn = (wgid % nig) / gsz; return true;
.LBB0_291:
	s_ashr_i32 s14, s16, 3
	s_add_i32 s14, s18, s14
	s_mul_hi_i32 s15, s14, 0x30c30c31
	s_lshr_b32 s16, s15, 31
	s_ashr_i32 s15, s15, 5
	s_add_i32 s15, s15, s16
	s_lshl_b32 s16, s15, 3
	s_sub_i32 s17, 0x84, s16
	s_min_i32 s17, s17, 8
	s_mulk_i32 s15, 0xa8
	s_sub_i32 s15, s14, s15
	s_cmp_eq_u32 s17, 8
	s_cselect_b32 s18, 3, 2
	s_lshr_b32 s14, s15, s18
	s_mul_i32 s17, s14, s17
	s_sub_i32 s15, s15, s17
	s_add_i32 s16, s16, s15

;     __host__ __device__ bool next(int i, Unit& u) const {
;         const long L = (long)i * G + c; if (L >= nwg) return false;
;         if (sl) { if (i > 0) return false; u.pm = ((int)L & 15) >> 2; u.pn = (int)L & 3; return true; }
;         int wgid = (int)L; { const int q = nwg / NXCD, r = nwg % NXCD, xcd = wgid % NXCD, off = wgid / NXCD; wgid = (xcd < r ? xcd * (q + 1) : r * (q + 1) + (xcd - r) * q) + off; }
;         const int nig = WGM * nN, gid = wgid / nig, fm = gid * WGM, gsz = (nM - fm) < WGM ? (nM - fm) : WGM;
;         u.pm = fm + ((wgid % nig) % gsz); u.pn = (wgid % nig) / gsz; return true;
; template <class Epi, class Sched, bool ALIGN_EPI = false, bool SP2 = false>
; __device__ __forceinline__ void gemm_phase(PG8_LAS unsigned char* lds, const Gemm g, const Sched& S, const Epi& E, const int tid) {
;     ...
;         const bool has_next = S.next(ui + 1, nxt);
.LBB0_519:
	s_add_i32 s44, s44, 1
	s_mul_i32 s2, s44, s30
	s_mul_hi_u32 s3, s44, s28
	s_add_i32 s3, s3, s2
	s_mul_i32 s2, s44, s28
	s_add_u32 s14, s2, s33
	s_addc_u32 s15, s3, s97
	v_cmp_gt_i64_e32 vcc, s[14:15], v[156:157]
	v_cmp_lt_i64_e64 s[2:3], s[14:15], v[154:155]
	s_cbranch_vccnz .LBB0_521
	s_ashr_i32 s10, s14, 31
	s_lshr_b32 s10, s10, 29
	s_add_i32 s10, s14, s10
	s_ashr_i32 s11, s10, 3
	s_and_b32 s10, s10, -8
	s_sub_i32 s10, s14, s10
	s_cmp_lt_i32 s10, 0
	s_cselect_b32 s12, s55, 0x16b
	s_mul_i32 s10, s10, s12
	s_add_i32 s10, s10, s11
	s_mul_hi_i32 s11, s10, 0x2e8ba2e9
	s_lshr_b32 s12, s11, 31
	s_ashr_i32 s11, s11, 5
	s_add_i32 s11, s11, s12
	s_lshl_b32 s12, s11, 3
	s_sub_i32 s13, 0x84, s12
	s_min_i32 s13, s13, 8
	s_mulk_i32 s11, 0xb0
	s_sub_i32 s11, s10, s11
	s_cmp_eq_u32 s13, 8
	s_cselect_b32 s14, 3, 2
	s_lshr_b32 s10, s11, s14
	s_mul_i32 s13, s10, s13
	s_sub_i32 s11, s11, s13
	s_add_i32 s12, s12, s11

; __device__ __forceinline__ unsigned cvt_pk_bf16(float lo, float hi) { f32x2 v = {lo, hi}; bf16x2_t b = __builtin_convertvector(v, bf16x2_t); return __builtin_bit_cast(unsigned, b); }
; __device__ __forceinline__ float silu_f(float g) { return g * __builtin_amdgcn_rcpf(1.0f + __expf(-g)); }
;     __device__ __forceinline__ void operator()(const AccT& acc, const pg8::Unit& u, int wr, int wc, int fr, int fq) const {
;         const int row0 = u.pm * 256 + wr * 64 + fr, col0 = u.pn * 128 + wc * 32 + 8 * fq;
; #pragma unroll
;         for (int ai = 0; ai < 2; ++ai)
; #pragma unroll
;             for (int m = 0; m < 4; ++m) {
;                 bf16_t* p = O + (size_t)(row0 + ai * 128 + m * 16) * DFF + col0;
;                 const f32x4 g0 = acc[ai][0][m][0], g1 = acc[ai][0][m][1], u0 = acc[ai][1][m][0], u1 = acc[ai][1][m][1];
;                 u32x4 w;
;                 w.x = cvt_pk_bf16(silu_f(g0[0]) * u0[0], silu_f(g0[1]) * u0[1]); w.y = cvt_pk_bf16(silu_f(g0[2]) * u0[2], silu_f(g0[3]) * u0[3]);
;                 w.z = cvt_pk_bf16(silu_f(g1[0]) * u1[0], silu_f(g1[1]) * u1[1]); w.w = cvt_pk_bf16(silu_f(g1[2]) * u1[2], silu_f(g1[3]) * u1[3]);
;                 *(u32x4*)p = w;
;             }
;     }
.LBB0_525:
	s_mov_b32 s68, 0xbfb8aa3b
	s_mov_b32 s69, 0xbfb8aa3b
	s_mov_b32 s70, 1.0
	s_mov_b32 s71, 1.0
	v_lshl_add_u32 v165, s46, 8, v3
	v_lshl_or_b32 v144, s45, 7, v147
	v_ashrrev_i32_e32 v145, 31, v144
	v_mov_b64_e32 v[142:143], s[4:5]
	v_mad_i64_i32 v[166:167], s[18:19], v165, s56, v[142:143]
	v_lshlrev_b64 v[144:145], 1, v[144:145]
	v_lshl_add_u64 v[166:167], v[166:167], 0, v[144:145]
	s_andn2_b64 vcc, exec, s[2:3]
	s_mov_b64 s[72:73], 0x16000
	v_lshl_add_u64 v[186:187], v[166:167], 0, s[72:73]
	v_pk_mul_f32 v[170:171], v[128:129], s[68:69]
	v_pk_mul_f32 v[172:173], v[130:131], s[68:69]
	v_pk_mul_f32 v[174:175], v[120:121], s[68:69]
	v_pk_mul_f32 v[176:177], v[122:123], s[68:69]
	v_exp_f32_e32 v170, v170
	v_exp_f32_e32 v171, v171
	v_exp_f32_e32 v172, v172
	v_exp_f32_e32 v173, v173
	v_exp_f32_e32 v174, v174
	v_exp_f32_e32 v175, v175
	v_exp_f32_e32 v176, v176
	v_exp_f32_e32 v177, v177
	v_pk_add_f32 v[170:171], v[170:171], s[70:71]
	v_pk_add_f32 v[172:173], v[172:173], s[70:71]
	v_pk_add_f32 v[174:175], v[174:175], s[70:71]
	v_pk_add_f32 v[176:177], v[176:177], s[70:71]
	v_rcp_f32_e32 v170, v170
	v_rcp_f32_e32 v171, v171
	v_rcp_f32_e32 v172, v172
	v_rcp_f32_e32 v173, v173
	v_rcp_f32_e32 v174, v174
	v_rcp_f32_e32 v175, v175
	v_rcp_f32_e32 v176, v176
	v_rcp_f32_e32 v177, v177
	v_pk_mul_f32 v[170:171], v[128:129], v[170:171]
	v_pk_mul_f32 v[172:173], v[130:131], v[172:173]
	v_pk_mul_f32 v[174:175], v[120:121], v[174:175]
	v_pk_mul_f32 v[176:177], v[122:123], v[176:177]
	v_pk_mul_f32 v[170:171], v[170:171], v[124:125]
	v_pk_mul_f32 v[172:173], v[172:173], v[126:127]
	v_pk_mul_f32 v[174:175], v[174:175], v[116:117]
	v_pk_mul_f32 v[176:177], v[176:177], v[118:119]
	v_cvt_pk_bf16_f32 v178, v170, v171
	v_cvt_pk_bf16_f32 v179, v172, v173
	v_cvt_pk_bf16_f32 v180, v174, v175
	v_cvt_pk_bf16_f32 v181, v176, v177
	global_store_dwordx4 v[166:167], v[178:181], off
	s_mov_b64 s[72:73], 0x2c000
	v_lshl_add_u64 v[188:189], v[166:167], 0, s[72:73]
	v_pk_mul_f32 v[170:171], v[112:113], s[68:69]
	v_pk_mul_f32 v[172:173], v[114:115], s[68:69]
	v_pk_mul_f32 v[174:175], v[104:105], s[68:69]
	v_pk_mul_f32 v[176:177], v[106:107], s[68:69]
	v_exp_f32_e32 v170, v170
	v_exp_f32_e32 v171, v171
	v_exp_f32_e32 v172, v172
	v_exp_f32_e32 v173, v173
	v_exp_f32_e32 v174, v174
	v_exp_f32_e32 v175, v175
	v_exp_f32_e32 v176, v176
	v_exp_f32_e32 v177, v177
	v_pk_add_f32 v[170:171], v[170:171], s[70:71]
	v_pk_add_f32 v[172:173], v[172:173], s[70:71]
	v_pk_add_f32 v[174:175], v[174:175], s[70:71]
	v_pk_add_f32 v[176:177], v[176:177], s[70:71]
	v_rcp_f32_e32 v170, v170
	v_rcp_f32_e32 v171, v171
	v_rcp_f32_e32 v172, v172
	v_rcp_f32_e32 v173, v173
	v_rcp_f32_e32 v174, v174
	v_rcp_f32_e32 v175, v175
	v_rcp_f32_e32 v176, v176
	v_rcp_f32_e32 v177, v177
	v_pk_mul_f32 v[170:171], v[112:113], v[170:171]
	v_pk_mul_f32 v[172:173], v[114:115], v[172:173]
	v_pk_mul_f32 v[174:175], v[104:105], v[174:175]
	v_pk_mul_f32 v[176:177], v[106:107], v[176:177]
	v_pk_mul_f32 v[170:171], v[170:171], v[108:109]
	v_pk_mul_f32 v[172:173], v[172:173], v[110:111]
	v_pk_mul_f32 v[174:175], v[174:175], v[100:101]
	v_pk_mul_f32 v[176:177], v[176:177], v[102:103]
	v_cvt_pk_bf16_f32 v182, v170, v171
	v_cvt_pk_bf16_f32 v183, v172, v173
	v_cvt_pk_bf16_f32 v184, v174, v175
	v_cvt_pk_bf16_f32 v185, v176, v177
	global_store_dwordx4 v[186:187], v[182:185], off
	s_mov_b64 s[72:73], 0x42000
	v_lshl_add_u64 v[190:191], v[166:167], 0, s[72:73]
	v_pk_mul_f32 v[170:171], v[96:97], s[68:69]
	v_pk_mul_f32 v[172:173], v[98:99], s[68:69]
	v_pk_mul_f32 v[174:175], v[88:89], s[68:69]
	v_pk_mul_f32 v[176:177], v[90:91], s[68:69]
	v_exp_f32_e32 v170, v170
	v_exp_f32_e32 v171, v171
	v_exp_f32_e32 v172, v172
	v_exp_f32_e32 v173, v173
	v_exp_f32_e32 v174, v174
	v_exp_f32_e32 v175, v175
	v_exp_f32_e32 v176, v176
	v_exp_f32_e32 v177, v177
	v_pk_add_f32 v[170:171], v[170:171], s[70:71]
	v_pk_add_f32 v[172:173], v[172:173], s[70:71]
	v_pk_add_f32 v[174:175], v[174:175], s[70:71]
	v_pk_add_f32 v[176:177], v[176:177], s[70:71]
	v_rcp_f32_e32 v170, v170
	v_rcp_f32_e32 v171, v171
	v_rcp_f32_e32 v172, v172
	v_rcp_f32_e32 v173, v173
	v_rcp_f32_e32 v174, v174
	v_rcp_f32_e32 v175, v175
	v_rcp_f32_e32 v176, v176
	v_rcp_f32_e32 v177, v177
	v_pk_mul_f32 v[170:171], v[96:97], v[170:171]
	v_pk_mul_f32 v[172:173], v[98:99], v[172:173]
	v_pk_mul_f32 v[174:175], v[88:89], v[174:175]
	v_pk_mul_f32 v[176:177], v[90:91], v[176:177]
	v_pk_mul_f32 v[170:171], v[170:171], v[92:93]
	v_pk_mul_f32 v[172:173], v[172:173], v[94:95]
	v_pk_mul_f32 v[174:175], v[174:175], v[84:85]
	v_pk_mul_f32 v[176:177], v[176:177], v[86:87]
	v_cvt_pk_bf16_f32 v178, v170, v171
	v_cvt_pk_bf16_f32 v179, v172, v173
	v_cvt_pk_bf16_f32 v180, v174, v175
	v_cvt_pk_bf16_f32 v181, v176, v177
	global_store_dwordx4 v[188:189], v[178:181], off
	s_mov_b64 s[72:73], 0xb0000
	v_lshl_add_u64 v[192:193], v[166:167], 0, s[72:73]
	v_pk_mul_f32 v[170:171], v[80:81], s[68:69]
	v_pk_mul_f32 v[172:173], v[82:83], s[68:69]
	v_pk_mul_f32 v[174:175], v[72:73], s[68:69]
	v_pk_mul_f32 v[176:177], v[74:75], s[68:69]
	v_exp_f32_e32 v170, v170
	v_exp_f32_e32 v171, v171
	v_exp_f32_e32 v172, v172
	v_exp_f32_e32 v173, v173
	v_exp_f32_e32 v174, v174
	v_exp_f32_e32 v175, v175
	v_exp_f32_e32 v176, v176
	v_exp_f32_e32 v177, v177
	v_pk_add_f32 v[170:171], v[170:171], s[70:71]
	v_pk_add_f32 v[172:173], v[172:173], s[70:71]
	v_pk_add_f32 v[174:175], v[174:175], s[70:71]
	v_pk_add_f32 v[176:177], v[176:177], s[70:71]
	v_rcp_f32_e32 v170, v170
	v_rcp_f32_e32 v171, v171
	v_rcp_f32_e32 v172, v172
	v_rcp_f32_e32 v173, v173
	v_rcp_f32_e32 v174, v174
	v_rcp_f32_e32 v175, v175
	v_rcp_f32_e32 v176, v176
	v_rcp_f32_e32 v177, v177
; __device__ __forceinline__ unsigned cvt_pk_bf16(float lo, float hi) { f32x2 v = {lo, hi}; bf16x2_t b = __builtin_convertvector(v, bf16x2_t); return __builtin_bit_cast(unsigned, b); }
; __device__ __forceinline__ float silu_f(float g) { return g * __builtin_amdgcn_rcpf(1.0f + __expf(-g)); }
;     __device__ __forceinline__ void operator()(const AccT& acc, const pg8::Unit& u, int wr, int wc, int fr, int fq) const {
;         const int row0 = u.pm * 256 + wr * 64 + fr, col0 = u.pn * 128 + wc * 32 + 8 * fq;
; #pragma unroll
;         for (int ai = 0; ai < 2; ++ai)
; #pragma unroll
;             for (int m = 0; m < 4; ++m) {
;                 bf16_t* p = O + (size_t)(row0 + ai * 128 + m * 16) * DFF + col0;
;                 const f32x4 g0 = acc[ai][0][m][0], g1 = acc[ai][0][m][1], u0 = acc[ai][1][m][0], u1 = acc[ai][1][m][1];
;                 u32x4 w;
;                 w.x = cvt_pk_bf16(silu_f(g0[0]) * u0[0], silu_f(g0[1]) * u0[1]); w.y = cvt_pk_bf16(silu_f(g0[2]) * u0[2], silu_f(g0[3]) * u0[3]);
;                 w.z = cvt_pk_bf16(silu_f(g1[0]) * u1[0], silu_f(g1[1]) * u1[1]); w.w = cvt_pk_bf16(silu_f(g1[2]) * u1[2], silu_f(g1[3]) * u1[3]);
;                 *(u32x4*)p = w;
;             }
;     }
	v_pk_mul_f32 v[170:171], v[80:81], v[170:171]
	v_pk_mul_f32 v[172:173], v[82:83], v[172:173]
	v_pk_mul_f32 v[174:175], v[72:73], v[174:175]
	v_pk_mul_f32 v[176:177], v[74:75], v[176:177]
	v_pk_mul_f32 v[170:171], v[170:171], v[76:77]
	v_pk_mul_f32 v[172:173], v[172:173], v[78:79]
	v_pk_mul_f32 v[174:175], v[174:175], v[68:69]
	v_pk_mul_f32 v[176:177], v[176:177], v[70:71]
	v_cvt_pk_bf16_f32 v182, v170, v171
	v_cvt_pk_bf16_f32 v183, v172, v173
	v_cvt_pk_bf16_f32 v184, v174, v175
	v_cvt_pk_bf16_f32 v185, v176, v177
	global_store_dwordx4 v[190:191], v[182:185], off
	s_mov_b64 s[72:73], 0xc6000
	v_lshl_add_u64 v[194:195], v[166:167], 0, s[72:73]
	v_pk_mul_f32 v[170:171], v[64:65], s[68:69]
	v_pk_mul_f32 v[172:173], v[66:67], s[68:69]
	v_pk_mul_f32 v[174:175], v[56:57], s[68:69]
	v_pk_mul_f32 v[176:177], v[58:59], s[68:69]
	v_exp_f32_e32 v170, v170
	v_exp_f32_e32 v171, v171
	v_exp_f32_e32 v172, v172
	v_exp_f32_e32 v173, v173
	v_exp_f32_e32 v174, v174
	v_exp_f32_e32 v175, v175
	v_exp_f32_e32 v176, v176
	v_exp_f32_e32 v177, v177
	v_pk_add_f32 v[170:171], v[170:171], s[70:71]
	v_pk_add_f32 v[172:173], v[172:173], s[70:71]
	v_pk_add_f32 v[174:175], v[174:175], s[70:71]
	v_pk_add_f32 v[176:177], v[176:177], s[70:71]
	v_rcp_f32_e32 v170, v170
	v_rcp_f32_e32 v171, v171
	v_rcp_f32_e32 v172, v172
	v_rcp_f32_e32 v173, v173
	v_rcp_f32_e32 v174, v174
	v_rcp_f32_e32 v175, v175
	v_rcp_f32_e32 v176, v176
	v_rcp_f32_e32 v177, v177
	v_pk_mul_f32 v[170:171], v[64:65], v[170:171]
	v_pk_mul_f32 v[172:173], v[66:67], v[172:173]
	v_pk_mul_f32 v[174:175], v[56:57], v[174:175]
	v_pk_mul_f32 v[176:177], v[58:59], v[176:177]
	v_pk_mul_f32 v[170:171], v[170:171], v[60:61]
	v_pk_mul_f32 v[172:173], v[172:173], v[62:63]
	v_pk_mul_f32 v[174:175], v[174:175], v[52:53]
	v_pk_mul_f32 v[176:177], v[176:177], v[54:55]
	v_cvt_pk_bf16_f32 v178, v170, v171
	v_cvt_pk_bf16_f32 v179, v172, v173
	v_cvt_pk_bf16_f32 v180, v174, v175
	v_cvt_pk_bf16_f32 v181, v176, v177
	global_store_dwordx4 v[192:193], v[178:181], off
	s_mov_b64 s[72:73], 0xdc000
	v_lshl_add_u64 v[196:197], v[166:167], 0, s[72:73]
	v_pk_mul_f32 v[170:171], v[48:49], s[68:69]
	v_pk_mul_f32 v[172:173], v[50:51], s[68:69]
	v_pk_mul_f32 v[174:175], v[40:41], s[68:69]
	v_pk_mul_f32 v[176:177], v[42:43], s[68:69]
	v_exp_f32_e32 v170, v170
	v_exp_f32_e32 v171, v171
	v_exp_f32_e32 v172, v172
	v_exp_f32_e32 v173, v173
	v_exp_f32_e32 v174, v174
	v_exp_f32_e32 v175, v175
	v_exp_f32_e32 v176, v176
	v_exp_f32_e32 v177, v177
	v_pk_add_f32 v[170:171], v[170:171], s[70:71]
	v_pk_add_f32 v[172:173], v[172:173], s[70:71]
	v_pk_add_f32 v[174:175], v[174:175], s[70:71]
	v_pk_add_f32 v[176:177], v[176:177], s[70:71]
	v_rcp_f32_e32 v170, v170
	v_rcp_f32_e32 v171, v171
	v_rcp_f32_e32 v172, v172
	v_rcp_f32_e32 v173, v173
	v_rcp_f32_e32 v174, v174
	v_rcp_f32_e32 v175, v175
	v_rcp_f32_e32 v176, v176
	v_rcp_f32_e32 v177, v177
	v_pk_mul_f32 v[170:171], v[48:49], v[170:171]
	v_pk_mul_f32 v[172:173], v[50:51], v[172:173]
	v_pk_mul_f32 v[174:175], v[40:41], v[174:175]
	v_pk_mul_f32 v[176:177], v[42:43], v[176:177]
	v_pk_mul_f32 v[170:171], v[170:171], v[44:45]
	v_pk_mul_f32 v[172:173], v[172:173], v[46:47]
	v_pk_mul_f32 v[174:175], v[174:175], v[36:37]
	v_pk_mul_f32 v[176:177], v[176:177], v[38:39]
	v_cvt_pk_bf16_f32 v182, v170, v171
	v_cvt_pk_bf16_f32 v183, v172, v173
	v_cvt_pk_bf16_f32 v184, v174, v175
	v_cvt_pk_bf16_f32 v185, v176, v177
	global_store_dwordx4 v[194:195], v[182:185], off
	s_mov_b64 s[72:73], 0xf2000
	v_lshl_add_u64 v[198:199], v[166:167], 0, s[72:73]
	s_mov_b64 s[18:19], -1
	v_pk_mul_f32 v[170:171], v[32:33], s[68:69]
	v_pk_mul_f32 v[172:173], v[34:35], s[68:69]
	v_pk_mul_f32 v[174:175], v[24:25], s[68:69]
	v_pk_mul_f32 v[176:177], v[26:27], s[68:69]
	v_exp_f32_e32 v170, v170
	v_exp_f32_e32 v171, v171
	v_exp_f32_e32 v172, v172
	v_exp_f32_e32 v173, v173
	v_exp_f32_e32 v174, v174
	v_exp_f32_e32 v175, v175
	v_exp_f32_e32 v176, v176
	v_exp_f32_e32 v177, v177
	v_pk_add_f32 v[170:171], v[170:171], s[70:71]
	v_pk_add_f32 v[172:173], v[172:173], s[70:71]
	v_pk_add_f32 v[174:175], v[174:175], s[70:71]
	v_pk_add_f32 v[176:177], v[176:177], s[70:71]
	v_rcp_f32_e32 v170, v170
	v_rcp_f32_e32 v171, v171
	v_rcp_f32_e32 v172, v172
	v_rcp_f32_e32 v173, v173
	v_rcp_f32_e32 v174, v174
	v_rcp_f32_e32 v175, v175
	v_rcp_f32_e32 v176, v176
	v_rcp_f32_e32 v177, v177
	v_pk_mul_f32 v[170:171], v[32:33], v[170:171]
	v_pk_mul_f32 v[172:173], v[34:35], v[172:173]
	v_pk_mul_f32 v[174:175], v[24:25], v[174:175]
	v_pk_mul_f32 v[176:177], v[26:27], v[176:177]
	v_pk_mul_f32 v[170:171], v[170:171], v[28:29]
	v_pk_mul_f32 v[172:173], v[172:173], v[30:31]
	v_pk_mul_f32 v[174:175], v[174:175], v[20:21]
	v_pk_mul_f32 v[176:177], v[176:177], v[22:23]
	v_cvt_pk_bf16_f32 v178, v170, v171
	v_cvt_pk_bf16_f32 v179, v172, v173
	v_cvt_pk_bf16_f32 v180, v174, v175
	v_cvt_pk_bf16_f32 v181, v176, v177
	global_store_dwordx4 v[196:197], v[178:181], off
	v_pk_mul_f32 v[170:171], v[16:17], s[68:69]
	v_pk_mul_f32 v[172:173], v[18:19], s[68:69]
	v_pk_mul_f32 v[174:175], v[8:9], s[68:69]
	v_pk_mul_f32 v[176:177], v[10:11], s[68:69]
	v_exp_f32_e32 v170, v170
	v_exp_f32_e32 v171, v171
	v_exp_f32_e32 v172, v172
	v_exp_f32_e32 v173, v173
	v_exp_f32_e32 v174, v174
	v_exp_f32_e32 v175, v175
	v_exp_f32_e32 v176, v176
	v_exp_f32_e32 v177, v177
	v_pk_add_f32 v[170:171], v[170:171], s[70:71]
	v_pk_add_f32 v[172:173], v[172:173], s[70:71]
	v_pk_add_f32 v[174:175], v[174:175], s[70:71]
	v_pk_add_f32 v[176:177], v[176:177], s[70:71]
	v_rcp_f32_e32 v170, v170
	v_rcp_f32_e32 v171, v171
	v_rcp_f32_e32 v172, v172
	v_rcp_f32_e32 v173, v173
	v_rcp_f32_e32 v174, v174
	v_rcp_f32_e32 v175, v175
	v_rcp_f32_e32 v176, v176
	v_rcp_f32_e32 v177, v177
	v_pk_mul_f32 v[170:171], v[16:17], v[170:171]
	v_pk_mul_f32 v[172:173], v[18:19], v[172:173]
	v_pk_mul_f32 v[174:175], v[8:9], v[174:175]
	v_pk_mul_f32 v[176:177], v[10:11], v[176:177]
	v_pk_mul_f32 v[170:171], v[170:171], v[12:13]
	v_pk_mul_f32 v[172:173], v[172:173], v[14:15]
	v_pk_mul_f32 v[174:175], v[174:175], v[4:5]
	v_pk_mul_f32 v[176:177], v[176:177], v[6:7]
	v_cvt_pk_bf16_f32 v182, v170, v171
	v_cvt_pk_bf16_f32 v183, v172, v173
	v_cvt_pk_bf16_f32 v184, v174, v175
	v_cvt_pk_bf16_f32 v185, v176, v177
	global_store_dwordx4 v[198:199], v[182:185], off
	s_cbranch_vccnz .LBB0_518
	s_andn2_b64 vcc, exec, s[6:7]
	s_cbranch_vccnz .LBB0_517
	s_barrier
	s_branch .LBB0_517
